# grid barrier: the last XCD leader bumps every XCD's generation word directly (16 fire-and-forget atomics) so the other leaders and all waiters poll their own XCD line; removes the TOPGEN->leader->XGEN
# speedup vs baseline: 1.0078x; 1.0056x over previous
.LBB0_246:
	s_or_b64 exec, exec, s[6:7]
	v_cvt_f32_u32_e32 v3, v0
	s_waitcnt vmcnt(0)
	v_readfirstlane_b32 s4, v2
	s_add_u32 s6, s84, 0x5903500
	s_addc_u32 s7, s85, 0
	v_rcp_iflag_f32_e32 v3, v3
	v_add_u32_e32 v1, s4, v1
	v_add_u32_e32 v4, 1, v1
	s_mov_b64 s[8:9], -1
	v_mul_f32_e32 v2, 0x4f7ffffe, v3
	v_cvt_u32_f32_e32 v2, v2
	v_sub_u32_e32 v3, 0, v0
	v_mul_lo_u32 v3, v3, v2
	v_mul_hi_u32 v3, v2, v3
	v_add_u32_e32 v2, v2, v3
	v_mul_hi_u32 v2, v1, v2
	v_mul_lo_u32 v3, v2, v0
	v_sub_u32_e32 v1, v1, v3
	v_add_u32_e32 v5, 1, v2
	v_cmp_ge_u32_e32 vcc, v1, v0
	v_sub_u32_e32 v3, v1, v0
	s_nop 0
	v_cndmask_b32_e32 v2, v2, v5, vcc
	v_cndmask_b32_e32 v1, v1, v3, vcc
	v_add_u32_e32 v3, 1, v2
	v_cmp_ge_u32_e32 vcc, v1, v0
	s_nop 1
	v_cndmask_b32_e32 v2, v2, v3, vcc
	v_mul_lo_u32 v1, v0, v2
	v_add_u32_e32 v0, v1, v0
	v_cmp_ne_u32_e32 vcc, v4, v0
	v_mov_b64_e32 v[0:1], s[6:7]
	s_cbranch_vccnz .Lmy_notlast_0
	v_mov_b32_e32 v3, 0x5902400
	v_mov_b32_e32 v5, 1
	global_atomic_add v3, v5, s[84:85]
	global_atomic_add v3, v5, s[84:85] offset:256
	global_atomic_add v3, v5, s[84:85] offset:512
	global_atomic_add v3, v5, s[84:85] offset:768
	global_atomic_add v3, v5, s[84:85] offset:1024
	global_atomic_add v3, v5, s[84:85] offset:1280
	global_atomic_add v3, v5, s[84:85] offset:1536
	global_atomic_add v3, v5, s[84:85] offset:1792
	global_atomic_add v3, v5, s[84:85] offset:2048
	global_atomic_add v3, v5, s[84:85] offset:2304
	global_atomic_add v3, v5, s[84:85] offset:2560
	global_atomic_add v3, v5, s[84:85] offset:2816
	global_atomic_add v3, v5, s[84:85] offset:3072
	global_atomic_add v3, v5, s[84:85] offset:3328
	global_atomic_add v3, v5, s[84:85] offset:3584
	global_atomic_add v3, v5, s[84:85] offset:3840
.Lmy_notlast_0:
	s_and_saveexec_b64 s[4:5], vcc
	s_cbranch_execz .LBB0_258
	v_mov_b32_e32 v0, 0
	v_mov_b32_e32 v6, 0x2000
	global_load_dword v1, v6, s[2:3] offset:1024 sc1
	s_mov_b64 s[12:13], 0
	s_waitcnt vmcnt(0)
	v_cmp_eq_u32_e32 vcc, v1, v2
	s_and_saveexec_b64 s[10:11], vcc
	s_cbranch_execz .LBB0_257
	s_add_u32 s8, s84, 0x5900200
	s_addc_u32 s9, s85, 0
	s_mov_b32 s22, 1
	s_branch .LBB0_250

.LBB0_252:
	global_load_dword v1, v6, s[2:3] offset:1024 sc1
	s_add_i32 s22, s22, 1
	s_mov_b64 s[16:17], -1
	s_waitcnt vmcnt(0)
	v_cmp_ne_u32_e32 vcc, v1, v2
	s_orn2_b64 s[20:21], vcc, exec
	s_branch .LBB0_249

.LBB0_260:
	s_or_b64 exec, exec, s[4:5]
	s_mov_b64 s[4:5], exec
	v_mbcnt_lo_u32_b32 v0, s4, 0
	v_mbcnt_hi_u32_b32 v0, s5, v0
	v_cmp_eq_u32_e32 vcc, 0, v0
	s_waitcnt vmcnt(0)
	s_and_saveexec_b64 s[6:7], vcc
	s_cbranch_execz .LBB0_262
	s_bcnt1_i32_b64 s4, s[4:5]
	v_mov_b32_e32 v0, 0x2000
	v_mov_b32_e32 v1, s4
.LBB0_262:
	s_or_b64 exec, exec, s[6:7]
	s_waitcnt vmcnt(0)

.LBB0_331:
	s_or_b64 exec, exec, s[4:5]
	s_mov_b64 s[4:5], exec
	v_mbcnt_lo_u32_b32 v0, s4, 0
	v_mbcnt_hi_u32_b32 v0, s5, v0
	v_cmp_eq_u32_e32 vcc, 0, v0
	s_waitcnt vmcnt(0)
	s_and_saveexec_b64 s[6:7], vcc
	s_cbranch_execz .LBB0_333
	s_bcnt1_i32_b64 s4, s[4:5]
	v_mov_b32_e32 v0, 0x2000
	v_mov_b32_e32 v1, s4
.LBB0_333:
	s_or_b64 exec, exec, s[6:7]
	s_waitcnt vmcnt(0)

.LBB0_511:
	s_or_b64 exec, exec, s[4:5]
	s_mov_b64 s[4:5], exec
	v_mbcnt_lo_u32_b32 v0, s4, 0
	v_mbcnt_hi_u32_b32 v0, s5, v0
	v_cmp_eq_u32_e32 vcc, 0, v0
	s_waitcnt vmcnt(0)
	s_and_saveexec_b64 s[6:7], vcc
	s_cbranch_execz .LBB0_513
	s_bcnt1_i32_b64 s4, s[4:5]
	v_mov_b32_e32 v0, 0x2000
	v_mov_b32_e32 v1, s4
.LBB0_513:
	s_or_b64 exec, exec, s[6:7]
	s_waitcnt vmcnt(0)

.LBB0_928:
	s_or_b64 exec, exec, s[4:5]
	s_mov_b64 s[4:5], exec
	v_mbcnt_lo_u32_b32 v0, s4, 0
	v_mbcnt_hi_u32_b32 v0, s5, v0
	v_cmp_eq_u32_e32 vcc, 0, v0
	s_waitcnt vmcnt(0)
	s_and_saveexec_b64 s[6:7], vcc
	s_cbranch_execz .LBB0_930
	s_bcnt1_i32_b64 s4, s[4:5]
	v_mov_b32_e32 v0, 0x2000
	v_mov_b32_e32 v1, s4
.LBB0_930:
	s_or_b64 exec, exec, s[6:7]
	s_waitcnt vmcnt(0)

.LBB0_1053:
	s_or_b64 exec, exec, s[4:5]
	s_mov_b64 s[4:5], exec
	v_mbcnt_lo_u32_b32 v0, s4, 0
	v_mbcnt_hi_u32_b32 v0, s5, v0
	v_cmp_eq_u32_e32 vcc, 0, v0
	s_waitcnt vmcnt(0)
	s_and_saveexec_b64 s[6:7], vcc
	s_cbranch_execz .LBB0_1055
	s_bcnt1_i32_b64 s4, s[4:5]
	v_mov_b32_e32 v0, 0x2000
	v_mov_b32_e32 v1, s4
.LBB0_1055:
	s_or_b64 exec, exec, s[6:7]
	s_waitcnt vmcnt(0)

.LBB0_1154:
	s_or_b64 exec, exec, s[4:5]
	s_mov_b64 s[4:5], exec
	v_mbcnt_lo_u32_b32 v0, s4, 0
	v_mbcnt_hi_u32_b32 v0, s5, v0
	v_cmp_eq_u32_e32 vcc, 0, v0
	s_waitcnt vmcnt(0)
	s_and_saveexec_b64 s[6:7], vcc
	s_cbranch_execz .LBB0_1156
	s_bcnt1_i32_b64 s4, s[4:5]
	v_mov_b32_e32 v0, 0x2000
	v_mov_b32_e32 v1, s4
.LBB0_1156:
	s_or_b64 exec, exec, s[6:7]
	s_waitcnt vmcnt(0)

.LBB0_1236:
	s_or_b64 exec, exec, s[4:5]
	s_mov_b64 s[4:5], exec
	v_mbcnt_lo_u32_b32 v0, s4, 0
	v_mbcnt_hi_u32_b32 v0, s5, v0
	v_cmp_eq_u32_e32 vcc, 0, v0
	s_waitcnt vmcnt(0)
	s_and_saveexec_b64 s[6:7], vcc
	s_cbranch_execz .LBB0_1238
	s_bcnt1_i32_b64 s4, s[4:5]
	v_mov_b32_e32 v0, 0x2000
	v_mov_b32_e32 v1, s4
.LBB0_1238:
	s_or_b64 exec, exec, s[6:7]
	s_waitcnt vmcnt(0)

.LBB0_1307:
	s_or_b64 exec, exec, s[4:5]
	s_mov_b64 s[4:5], exec
	v_mbcnt_lo_u32_b32 v0, s4, 0
	v_mbcnt_hi_u32_b32 v0, s5, v0
	v_cmp_eq_u32_e32 vcc, 0, v0
	s_waitcnt vmcnt(0)
	s_and_saveexec_b64 s[6:7], vcc
	s_cbranch_execz .LBB0_1309
	s_bcnt1_i32_b64 s4, s[4:5]
	v_mov_b32_e32 v0, 0x2000
	v_mov_b32_e32 v1, s4
.LBB0_1309:
	s_or_b64 exec, exec, s[6:7]
	s_waitcnt vmcnt(0)

.LBB0_1404:
	s_or_b64 exec, exec, s[4:5]
	s_mov_b64 s[4:5], exec
	v_mbcnt_lo_u32_b32 v0, s4, 0
	v_mbcnt_hi_u32_b32 v0, s5, v0
	v_cmp_eq_u32_e32 vcc, 0, v0
	s_waitcnt vmcnt(0)
	s_and_saveexec_b64 s[6:7], vcc
	s_cbranch_execz .LBB0_1406
	s_bcnt1_i32_b64 s4, s[4:5]
	v_mov_b32_e32 v0, 0x2000
	v_mov_b32_e32 v1, s4
.LBB0_1406:
	s_or_b64 exec, exec, s[6:7]
	s_waitcnt vmcnt(0)

.LBB0_1483:
	s_or_b64 exec, exec, s[4:5]
	s_mov_b64 s[4:5], exec
	v_mbcnt_lo_u32_b32 v0, s4, 0
	v_mbcnt_hi_u32_b32 v0, s5, v0
	v_cmp_eq_u32_e32 vcc, 0, v0
	s_waitcnt vmcnt(0)
	s_and_saveexec_b64 s[6:7], vcc
	s_cbranch_execz .LBB0_1485
	s_bcnt1_i32_b64 s4, s[4:5]
	v_mov_b32_e32 v0, 0x2000
	v_mov_b32_e32 v1, s4
.LBB0_1485:
	s_or_b64 exec, exec, s[6:7]
	s_waitcnt vmcnt(0)
